# grid barrier: waiting workgroups poll the cross-XCD generation word directly (one polling hop instead of two after the last arrival)
# baseline (speedup 1.0000x reference)
; DI unsigned xb_ld(unsigned* p) { return __hip_atomic_load(p, __ATOMIC_RELAXED, __HIP_MEMORY_SCOPE_AGENT); }
; DI unsigned xb_add(unsigned* p, unsigned v) { return __hip_atomic_fetch_add(p, v, __ATOMIC_RELAXED, __HIP_MEMORY_SCOPE_AGENT); }
; #define XB_SPIN(cond, bar) do { unsigned _sp = 0; while (cond) { __builtin_amdgcn_s_sleep(1); \
;     if ((++_sp & 255u) == 0u) { if (xb_ld(&(bar)[XB_TMO])) break; if (_sp > XB_SPIN_CAP) { atomicAdd(&(bar)[XB_TMO], 1u); break; } } } } while (0)
; DI void xcd_barrier(const XcdBarrier& b) {
;     ...
;         const unsigned old = xb_add(&bar[XB_XSUB(b.x)], 1u);
;         const unsigned gen = old / nloc;
;         if (old + 1u == (gen + 1u) * nloc) {
;             __builtin_amdgcn_fence(__ATOMIC_RELEASE, "agent");
;             asm volatile("s_waitcnt vmcnt(0)" ::: "memory");
;             const unsigned og = xb_add(&bar[XB_TOP], 1u);
;             const unsigned tg = og / nx;
;             if (og + 1u == (tg + 1u) * nx) xb_add(&bar[XB_TOPGEN], 1u);
;             else XB_SPIN(xb_ld(&bar[XB_TOPGEN]) == tg, bar);
;             __builtin_amdgcn_fence(__ATOMIC_ACQUIRE, "agent");
;             xb_add(&bar[XB_XGEN(b.x)], 1u);
;             asm volatile("s_waitcnt vmcnt(0)" ::: "memory");
;         } else {
;             XB_SPIN(xb_ld(&bar[XB_XGEN(b.x)]) == gen, bar);
.LBB0_173:
	s_or_b64 exec, exec, s[10:11]
	v_cvt_f32_u32_e32 v4, v2
	s_waitcnt vmcnt(0)
	v_readfirstlane_b32 s2, v3
	v_sub_u32_e32 v3, 0, v2
	v_rcp_iflag_f32_e32 v4, v4
	v_add_u32_e32 v5, s2, v0
	v_mul_f32_e32 v4, 0x4f7ffffe, v4
	v_cvt_u32_f32_e32 v4, v4
	v_mul_lo_u32 v0, v3, v4
	v_mul_hi_u32 v0, v4, v0
	v_add_u32_e32 v0, v4, v0
	v_mul_hi_u32 v0, v5, v0
	v_mul_lo_u32 v3, v0, v2
	v_sub_u32_e32 v3, v5, v3
	v_add_u32_e32 v4, 1, v0
	v_cmp_ge_u32_e32 vcc, v3, v2
	s_nop 1
	v_cndmask_b32_e32 v0, v0, v4, vcc
	v_sub_u32_e32 v4, v3, v2
	v_cndmask_b32_e32 v3, v3, v4, vcc
	v_add_u32_e32 v4, 1, v0
	v_cmp_ge_u32_e32 vcc, v3, v2
	v_add_u32_e32 v3, 1, v5
	s_nop 0
	v_cndmask_b32_e32 v0, v0, v4, vcc
	v_mul_lo_u32 v4, v2, v0
	v_add_u32_e32 v2, v4, v2
	v_cmp_ne_u32_e32 vcc, v3, v2
	s_and_saveexec_b64 s[2:3], vcc
	s_xor_b64 s[8:9], exec, s[2:3]
	s_cbranch_execz .LBB0_187
	s_waitcnt lgkmcnt(0)
	v_mov_b32_e32 v1, 0x4000
	global_load_dword v1, v1, s[56:57] offset:1280 sc1
	s_add_u32 s14, s56, 0x4500
	s_addc_u32 s15, s57, 0
	s_waitcnt vmcnt(0)
	v_cmp_eq_u32_e32 vcc, v1, v0
	s_and_saveexec_b64 s[10:11], vcc
	s_cbranch_execz .LBB0_186
	s_add_u32 s12, s56, 0x1200
	s_addc_u32 s13, s57, 0
	s_mov_b32 s2, 1
	s_mov_b64 s[18:19], 0
	v_mov_b32_e32 v1, 0
	s_branch .LBB0_177

; DI unsigned xb_add(unsigned* p, unsigned v) { return __hip_atomic_fetch_add(p, v, __ATOMIC_RELAXED, __HIP_MEMORY_SCOPE_AGENT); }
; DI void xcd_barrier(const XcdBarrier& b) {
;     ...
;             __builtin_amdgcn_fence(__ATOMIC_ACQUIRE, "agent");
;             xb_add(&bar[XB_XGEN(b.x)], 1u);
;             asm volatile("s_waitcnt vmcnt(0)" ::: "memory");
.LBB0_204:
	s_or_b64 exec, exec, s[8:9]
	s_mov_b64 s[8:9], exec
	v_mbcnt_lo_u32_b32 v0, s8, 0
	v_mbcnt_hi_u32_b32 v0, s9, v0
	v_cmp_eq_u32_e32 vcc, 0, v0
	s_waitcnt vmcnt(0)
	buffer_inv sc1
	s_and_saveexec_b64 s[10:11], vcc
	s_cbranch_execz .LBB0_206
	s_bcnt1_i32_b64 s2, s[8:9]
	v_mov_b32_e32 v0, 0x2000
	v_mov_b32_e32 v1, s2
.LBB0_206:
	s_or_b64 exec, exec, s[10:11]
	s_waitcnt vmcnt(0)

; DI unsigned xb_add(unsigned* p, unsigned v) { return __hip_atomic_fetch_add(p, v, __ATOMIC_RELAXED, __HIP_MEMORY_SCOPE_AGENT); }
; DI void xcd_barrier(const XcdBarrier& b) {
;     ...
;             __builtin_amdgcn_fence(__ATOMIC_ACQUIRE, "agent");
;             xb_add(&bar[XB_XGEN(b.x)], 1u);
;             asm volatile("s_waitcnt vmcnt(0)" ::: "memory");
.LBB0_529:
	s_or_b64 exec, exec, s[8:9]
	s_mov_b64 s[8:9], exec
	v_mbcnt_lo_u32_b32 v0, s8, 0
	v_mbcnt_hi_u32_b32 v0, s9, v0
	v_cmp_eq_u32_e32 vcc, 0, v0
	s_waitcnt vmcnt(0)
	buffer_inv sc1
	s_and_saveexec_b64 s[10:11], vcc
	s_cbranch_execz .LBB0_531
	s_bcnt1_i32_b64 s2, s[8:9]
	v_mov_b32_e32 v0, 0x2000
	v_mov_b32_e32 v1, s2
.LBB0_531:
	s_or_b64 exec, exec, s[10:11]
	s_waitcnt vmcnt(0)

; DI unsigned xb_add(unsigned* p, unsigned v) { return __hip_atomic_fetch_add(p, v, __ATOMIC_RELAXED, __HIP_MEMORY_SCOPE_AGENT); }
; DI void xcd_barrier(const XcdBarrier& b) {
;     ...
;             __builtin_amdgcn_fence(__ATOMIC_ACQUIRE, "agent");
;             xb_add(&bar[XB_XGEN(b.x)], 1u);
;             asm volatile("s_waitcnt vmcnt(0)" ::: "memory");
.LBB0_725:
	s_or_b64 exec, exec, s[8:9]
	s_mov_b64 s[8:9], exec
	v_mbcnt_lo_u32_b32 v0, s8, 0
	v_mbcnt_hi_u32_b32 v0, s9, v0
	v_cmp_eq_u32_e32 vcc, 0, v0
	s_waitcnt vmcnt(0)
	buffer_inv sc1
	s_and_saveexec_b64 s[10:11], vcc
	s_cbranch_execz .LBB0_727
	s_bcnt1_i32_b64 s2, s[8:9]
	v_mov_b32_e32 v0, 0x2000
	v_mov_b32_e32 v1, s2
.LBB0_727:
	s_or_b64 exec, exec, s[10:11]
	s_waitcnt vmcnt(0)

; DI unsigned xb_add(unsigned* p, unsigned v) { return __hip_atomic_fetch_add(p, v, __ATOMIC_RELAXED, __HIP_MEMORY_SCOPE_AGENT); }
; DI void xcd_barrier(const XcdBarrier& b) {
;     ...
;             __builtin_amdgcn_fence(__ATOMIC_ACQUIRE, "agent");
;             xb_add(&bar[XB_XGEN(b.x)], 1u);
;             asm volatile("s_waitcnt vmcnt(0)" ::: "memory");
.LBB0_902:
	s_or_b64 exec, exec, s[8:9]
	s_mov_b64 s[8:9], exec
	v_mbcnt_lo_u32_b32 v0, s8, 0
	v_mbcnt_hi_u32_b32 v0, s9, v0
	v_cmp_eq_u32_e32 vcc, 0, v0
	s_waitcnt vmcnt(0)
	buffer_inv sc1
	s_and_saveexec_b64 s[10:11], vcc
	s_cbranch_execz .LBB0_904
	s_bcnt1_i32_b64 s2, s[8:9]
	v_mov_b32_e32 v0, 0x2000
	v_mov_b32_e32 v1, s2
.LBB0_904:
	s_or_b64 exec, exec, s[10:11]
	s_waitcnt vmcnt(0)

; DI unsigned xb_add(unsigned* p, unsigned v) { return __hip_atomic_fetch_add(p, v, __ATOMIC_RELAXED, __HIP_MEMORY_SCOPE_AGENT); }
; DI void xcd_barrier(const XcdBarrier& b) {
;     ...
;             __builtin_amdgcn_fence(__ATOMIC_ACQUIRE, "agent");
;             xb_add(&bar[XB_XGEN(b.x)], 1u);
;             asm volatile("s_waitcnt vmcnt(0)" ::: "memory");
.LBB0_984:
	s_or_b64 exec, exec, s[8:9]
	s_mov_b64 s[8:9], exec
	v_mbcnt_lo_u32_b32 v0, s8, 0
	v_mbcnt_hi_u32_b32 v0, s9, v0
	v_cmp_eq_u32_e32 vcc, 0, v0
	s_waitcnt vmcnt(0)
	buffer_inv sc1
	s_and_saveexec_b64 s[10:11], vcc
	s_cbranch_execz .LBB0_986
	s_bcnt1_i32_b64 s2, s[8:9]
	v_mov_b32_e32 v0, 0x2000
	v_mov_b32_e32 v1, s2
.LBB0_986:
	s_or_b64 exec, exec, s[10:11]
	s_waitcnt vmcnt(0)

; DI unsigned xb_add(unsigned* p, unsigned v) { return __hip_atomic_fetch_add(p, v, __ATOMIC_RELAXED, __HIP_MEMORY_SCOPE_AGENT); }
; DI void xcd_barrier(const XcdBarrier& b) {
;     ...
;             __builtin_amdgcn_fence(__ATOMIC_ACQUIRE, "agent");
;             xb_add(&bar[XB_XGEN(b.x)], 1u);
;             asm volatile("s_waitcnt vmcnt(0)" ::: "memory");
.LBB0_1051:
	s_or_b64 exec, exec, s[8:9]
	s_mov_b64 s[8:9], exec
	v_mbcnt_lo_u32_b32 v0, s8, 0
	v_mbcnt_hi_u32_b32 v0, s9, v0
	v_cmp_eq_u32_e32 vcc, 0, v0
	s_waitcnt vmcnt(0)
	buffer_inv sc1
	s_and_saveexec_b64 s[10:11], vcc
	s_cbranch_execz .LBB0_1053
	s_bcnt1_i32_b64 s2, s[8:9]
	v_mov_b32_e32 v0, 0x2000
	v_mov_b32_e32 v1, s2
.LBB0_1053:
	s_or_b64 exec, exec, s[10:11]
	s_waitcnt vmcnt(0)

; DI unsigned xb_ld(unsigned* p) { return __hip_atomic_load(p, __ATOMIC_RELAXED, __HIP_MEMORY_SCOPE_AGENT); }
; DI unsigned xb_add(unsigned* p, unsigned v) { return __hip_atomic_fetch_add(p, v, __ATOMIC_RELAXED, __HIP_MEMORY_SCOPE_AGENT); }
; #define XB_SPIN(cond, bar) do { unsigned _sp = 0; while (cond) { __builtin_amdgcn_s_sleep(1); \
;     if ((++_sp & 255u) == 0u) { if (xb_ld(&(bar)[XB_TMO])) break; if (_sp > XB_SPIN_CAP) { atomicAdd(&(bar)[XB_TMO], 1u); break; } } } } while (0)
; DI void xcd_barrier(const XcdBarrier& b) {
;     ...
;         const unsigned old = xb_add(&bar[XB_XSUB(b.x)], 1u);
;         const unsigned gen = old / nloc;
;         if (old + 1u == (gen + 1u) * nloc) {
;             __builtin_amdgcn_fence(__ATOMIC_RELEASE, "agent");
;             asm volatile("s_waitcnt vmcnt(0)" ::: "memory");
;             const unsigned og = xb_add(&bar[XB_TOP], 1u);
;             const unsigned tg = og / nx;
;             if (og + 1u == (tg + 1u) * nx) xb_add(&bar[XB_TOPGEN], 1u);
;             else XB_SPIN(xb_ld(&bar[XB_TOPGEN]) == tg, bar);
;             __builtin_amdgcn_fence(__ATOMIC_ACQUIRE, "agent");
;             xb_add(&bar[XB_XGEN(b.x)], 1u);
;             asm volatile("s_waitcnt vmcnt(0)" ::: "memory");
;         } else {
;             XB_SPIN(xb_ld(&bar[XB_XGEN(b.x)]) == gen, bar);
.LBB0_1108:
	s_or_b64 exec, exec, s[10:11]
	v_cvt_f32_u32_e32 v4, v2
	s_waitcnt vmcnt(0)
	v_readfirstlane_b32 s2, v3
	v_sub_u32_e32 v3, 0, v2
	v_rcp_iflag_f32_e32 v4, v4
	v_add_u32_e32 v5, s2, v0
	v_mul_f32_e32 v4, 0x4f7ffffe, v4
	v_cvt_u32_f32_e32 v4, v4
	v_mul_lo_u32 v0, v3, v4
	v_mul_hi_u32 v0, v4, v0
	v_add_u32_e32 v0, v4, v0
	v_mul_hi_u32 v0, v5, v0
	v_mul_lo_u32 v3, v0, v2
	v_sub_u32_e32 v3, v5, v3
	v_add_u32_e32 v4, 1, v0
	v_cmp_ge_u32_e32 vcc, v3, v2
	s_nop 1
	v_cndmask_b32_e32 v0, v0, v4, vcc
	v_sub_u32_e32 v4, v3, v2
	v_cndmask_b32_e32 v3, v3, v4, vcc
	v_add_u32_e32 v4, 1, v0
	v_cmp_ge_u32_e32 vcc, v3, v2
	v_add_u32_e32 v3, 1, v5
	s_nop 0
	v_cndmask_b32_e32 v0, v0, v4, vcc
	v_mul_lo_u32 v4, v2, v0
	v_add_u32_e32 v2, v4, v2
	v_cmp_ne_u32_e32 vcc, v3, v2
	s_and_saveexec_b64 s[2:3], vcc
	s_xor_b64 s[8:9], exec, s[2:3]
	s_cbranch_execz .LBB0_1122
	s_waitcnt lgkmcnt(0)
	v_mov_b32_e32 v1, 0x4000
	global_load_dword v1, v1, s[56:57] offset:1280 sc1
	s_add_u32 s14, s56, 0x4500
	s_addc_u32 s15, s57, 0
	s_waitcnt vmcnt(0)
	v_cmp_eq_u32_e32 vcc, v1, v0
	s_and_saveexec_b64 s[10:11], vcc
	s_cbranch_execz .LBB0_1121
	s_add_u32 s12, s56, 0x1200
	s_addc_u32 s13, s57, 0
	s_mov_b32 s2, 1
	s_mov_b64 s[16:17], 0
	v_mov_b32_e32 v1, 0
	s_branch .LBB0_1112

; DI unsigned xb_add(unsigned* p, unsigned v) { return __hip_atomic_fetch_add(p, v, __ATOMIC_RELAXED, __HIP_MEMORY_SCOPE_AGENT); }
; DI void xcd_barrier(const XcdBarrier& b) {
;     ...
;             __builtin_amdgcn_fence(__ATOMIC_ACQUIRE, "agent");
;             xb_add(&bar[XB_XGEN(b.x)], 1u);
;             asm volatile("s_waitcnt vmcnt(0)" ::: "memory");
.LBB0_1139:
	s_or_b64 exec, exec, s[8:9]
	s_mov_b64 s[8:9], exec
	v_mbcnt_lo_u32_b32 v0, s8, 0
	v_mbcnt_hi_u32_b32 v0, s9, v0
	v_cmp_eq_u32_e32 vcc, 0, v0
	s_waitcnt vmcnt(0)
	buffer_inv sc1
	s_and_saveexec_b64 s[10:11], vcc
	s_cbranch_execz .LBB0_1141
	s_bcnt1_i32_b64 s2, s[8:9]
	v_mov_b32_e32 v0, 0x2000
	v_mov_b32_e32 v1, s2
.LBB0_1141:
	s_or_b64 exec, exec, s[10:11]
	s_waitcnt vmcnt(0)
